# PRO adaLN GEMV unrolled with weight loads 3 k-iterations ahead
# baseline (speedup 1.0000x reference)
.LBB0_1022:
	v_add_co_u32_e32 v92, vcc, 0xfff4c000, v20
	s_nop 1
	v_addc_co_u32_e32 v93, vcc, -1, v21, vcc
	global_load_dword v100, v[92:93], off
	v_add_co_u32_e32 v92, vcc, 0xfff58000, v20
	s_nop 1
	v_addc_co_u32_e32 v93, vcc, -1, v21, vcc
	global_load_dword v101, v[92:93], off
	v_add_co_u32_e32 v92, vcc, 0xfff64000, v20
	s_nop 1
	v_addc_co_u32_e32 v93, vcc, -1, v21, vcc
	global_load_dword v102, v[92:93], off
	v_add_co_u32_e32 v92, vcc, 0xfff70000, v20
	s_nop 1
	v_addc_co_u32_e32 v93, vcc, -1, v21, vcc
	global_load_dword v103, v[92:93], off
	v_add_co_u32_e32 v92, vcc, 0xfff7c000, v20
	s_nop 1
	v_addc_co_u32_e32 v93, vcc, -1, v21, vcc
	global_load_dword v104, v[92:93], off
	v_add_co_u32_e32 v92, vcc, 0xfff88000, v20
	s_nop 1
	v_addc_co_u32_e32 v93, vcc, -1, v21, vcc
	global_load_dword v105, v[92:93], off
	v_add_co_u32_e32 v92, vcc, 0xfff94000, v20
	s_nop 1
	v_addc_co_u32_e32 v93, vcc, -1, v21, vcc
	global_load_dword v106, v[92:93], off
	v_add_co_u32_e32 v92, vcc, 0xfffa0000, v20
	s_nop 1
	v_addc_co_u32_e32 v93, vcc, -1, v21, vcc
	global_load_dword v107, v[92:93], off
	v_add_co_u32_e32 v92, vcc, 0xfffac000, v20
	s_nop 1
	v_addc_co_u32_e32 v93, vcc, -1, v21, vcc
	global_load_dword v108, v[92:93], off
	v_add_co_u32_e32 v92, vcc, 0xfffb8000, v20
	s_nop 1
	v_addc_co_u32_e32 v93, vcc, -1, v21, vcc
	global_load_dword v109, v[92:93], off
	v_add_co_u32_e32 v92, vcc, 0xfffc4000, v20
	s_nop 1
	v_addc_co_u32_e32 v93, vcc, -1, v21, vcc
	global_load_dword v110, v[92:93], off
	v_add_co_u32_e32 v92, vcc, 0xfffd0000, v20
	s_nop 1
	v_addc_co_u32_e32 v93, vcc, -1, v21, vcc
	global_load_dword v111, v[92:93], off
	v_add_co_u32_e32 v92, vcc, 0xfffdc000, v20
	s_nop 1
	v_addc_co_u32_e32 v93, vcc, -1, v21, vcc
	global_load_dword v112, v[92:93], off
	v_add_co_u32_e32 v92, vcc, 0xfffe8000, v20
	s_nop 1
	v_addc_co_u32_e32 v93, vcc, -1, v21, vcc
	global_load_dword v113, v[92:93], off
	v_add_co_u32_e32 v92, vcc, 0xffff4000, v20
	s_nop 1
	v_addc_co_u32_e32 v93, vcc, -1, v21, vcc
	global_load_dword v114, v[92:93], off
	global_load_dword v115, v[20:21], off
	v_add_co_u32_e32 v92, vcc, 0xc000, v20
	s_nop 1
	v_addc_co_u32_e32 v93, vcc, 0, v21, vcc
	global_load_dword v116, v[92:93], off
	v_add_co_u32_e32 v92, vcc, 0x18000, v20
	s_nop 1
	v_addc_co_u32_e32 v93, vcc, 0, v21, vcc
	global_load_dword v117, v[92:93], off
	v_add_co_u32_e32 v92, vcc, 0x24000, v20
	s_nop 1
	v_addc_co_u32_e32 v93, vcc, 0, v21, vcc
	global_load_dword v118, v[92:93], off
	v_add_co_u32_e32 v92, vcc, 0x30000, v20
	s_nop 1
	v_addc_co_u32_e32 v93, vcc, 0, v21, vcc
	global_load_dword v119, v[92:93], off
	v_add_co_u32_e32 v92, vcc, 0x3c000, v20
	s_nop 1
	v_addc_co_u32_e32 v93, vcc, 0, v21, vcc
	global_load_dword v120, v[92:93], off
	v_add_co_u32_e32 v92, vcc, 0x48000, v20
	s_nop 1
	v_addc_co_u32_e32 v93, vcc, 0, v21, vcc
	global_load_dword v121, v[92:93], off
	v_add_co_u32_e32 v92, vcc, 0x54000, v20
	s_nop 1
	v_addc_co_u32_e32 v93, vcc, 0, v21, vcc
	global_load_dword v122, v[92:93], off
	v_add_co_u32_e32 v92, vcc, 0x60000, v20
	s_nop 1
	v_addc_co_u32_e32 v93, vcc, 0, v21, vcc
	global_load_dword v123, v[92:93], off
	v_add_co_u32_e32 v92, vcc, 0x6c000, v20
	s_nop 1
	v_addc_co_u32_e32 v93, vcc, 0, v21, vcc
	global_load_dword v124, v[92:93], off
	v_add_co_u32_e32 v92, vcc, 0x78000, v20
	s_nop 1
	v_addc_co_u32_e32 v93, vcc, 0, v21, vcc
	global_load_dword v125, v[92:93], off
	v_add_co_u32_e32 v92, vcc, 0x84000, v20
	s_nop 1
	v_addc_co_u32_e32 v93, vcc, 0, v21, vcc
	global_load_dword v126, v[92:93], off
	v_add_co_u32_e32 v92, vcc, 0x90000, v20
	s_nop 1
	v_addc_co_u32_e32 v93, vcc, 0, v21, vcc
	global_load_dword v127, v[92:93], off
	v_add_co_u32_e32 v92, vcc, 0x9c000, v20
	s_nop 1
	v_addc_co_u32_e32 v93, vcc, 0, v21, vcc
	global_load_dword v128, v[92:93], off
	v_add_co_u32_e32 v92, vcc, 0xa8000, v20
	s_nop 1
	v_addc_co_u32_e32 v93, vcc, 0, v21, vcc
	global_load_dword v129, v[92:93], off
	v_add_co_u32_e32 v92, vcc, 0xb4000, v20
	s_nop 1
	v_addc_co_u32_e32 v93, vcc, 0, v21, vcc
	global_load_dword v130, v[92:93], off
	v_add_co_u32_e32 v92, vcc, 0xc0000, v20
	s_nop 1
	v_addc_co_u32_e32 v93, vcc, 0, v21, vcc
	global_load_dword v131, v[92:93], off
	v_add_co_u32_e32 v92, vcc, 0xcc000, v20
	s_nop 1
	v_addc_co_u32_e32 v93, vcc, 0, v21, vcc
	global_load_dword v132, v[92:93], off
	v_add_co_u32_e32 v92, vcc, 0xd8000, v20
	s_nop 1
	v_addc_co_u32_e32 v93, vcc, 0, v21, vcc
	global_load_dword v133, v[92:93], off
	v_add_co_u32_e32 v92, vcc, 0xe4000, v20
	s_nop 1
	v_addc_co_u32_e32 v93, vcc, 0, v21, vcc
	global_load_dword v134, v[92:93], off
	v_add_co_u32_e32 v92, vcc, 0xf0000, v20
	s_nop 1
	v_addc_co_u32_e32 v93, vcc, 0, v21, vcc
	global_load_dword v135, v[92:93], off
	v_add_co_u32_e32 v92, vcc, 0xfc000, v20
	s_nop 1
	v_addc_co_u32_e32 v93, vcc, 0, v21, vcc
	global_load_dword v136, v[92:93], off
	v_add_co_u32_e32 v92, vcc, 0x108000, v20
	s_nop 1
	v_addc_co_u32_e32 v93, vcc, 0, v21, vcc
	global_load_dword v137, v[92:93], off
	v_add_co_u32_e32 v92, vcc, 0x114000, v20
	s_nop 1
	v_addc_co_u32_e32 v93, vcc, 0, v21, vcc
	global_load_dword v138, v[92:93], off
	v_add_co_u32_e32 v92, vcc, 0x120000, v20
	s_nop 1
	v_addc_co_u32_e32 v93, vcc, 0, v21, vcc
	global_load_dword v139, v[92:93], off
	v_add_co_u32_e32 v92, vcc, 0x12c000, v20
	s_nop 1
	v_addc_co_u32_e32 v93, vcc, 0, v21, vcc
	global_load_dword v140, v[92:93], off
	v_add_co_u32_e32 v92, vcc, 0x138000, v20
	s_nop 1
	v_addc_co_u32_e32 v93, vcc, 0, v21, vcc
	global_load_dword v141, v[92:93], off
	v_add_co_u32_e32 v92, vcc, 0x144000, v20
	s_nop 1
	v_addc_co_u32_e32 v93, vcc, 0, v21, vcc
	global_load_dword v142, v[92:93], off
	v_add_co_u32_e32 v92, vcc, 0x150000, v20
	s_nop 1
	v_addc_co_u32_e32 v93, vcc, 0, v21, vcc
	global_load_dword v143, v[92:93], off
	v_add_co_u32_e32 v92, vcc, 0x15c000, v20
	s_nop 1
	v_addc_co_u32_e32 v93, vcc, 0, v21, vcc
	global_load_dword v144, v[92:93], off
	v_add_co_u32_e32 v92, vcc, 0x168000, v20
	s_nop 1
	v_addc_co_u32_e32 v93, vcc, 0, v21, vcc
	global_load_dword v145, v[92:93], off
	v_add_co_u32_e32 v92, vcc, 0x174000, v20
	s_nop 1
	v_addc_co_u32_e32 v93, vcc, 0, v21, vcc
	global_load_dword v146, v[92:93], off
	v_add_co_u32_e32 v92, vcc, 0x180000, v20
	s_nop 1
	v_addc_co_u32_e32 v93, vcc, 0, v21, vcc
	global_load_dword v147, v[92:93], off
	ds_read_b128 v[54:57], v38 offset:0
	ds_read_b128 v[58:61], v38 offset:2048
	ds_read_b128 v[62:65], v38 offset:4096
	ds_read_b128 v[66:69], v38 offset:6144
	ds_read_b128 v[70:73], v38 offset:8192
	ds_read_b128 v[74:77], v38 offset:10240
	ds_read_b128 v[78:81], v38 offset:12288
	ds_read_b128 v[82:85], v38 offset:14336
	ds_read_b128 v[86:89], v38 offset:16384
	s_waitcnt vmcnt(32)
	v_add_co_u32_e32 v92, vcc, 0x18c000, v20
	s_nop 1
	v_addc_co_u32_e32 v93, vcc, 0, v21, vcc
	global_load_dword v148, v[92:93], off
	v_add_co_u32_e32 v92, vcc, 0x198000, v20
	s_nop 1
	v_addc_co_u32_e32 v93, vcc, 0, v21, vcc
	global_load_dword v149, v[92:93], off
	v_add_co_u32_e32 v92, vcc, 0x1a4000, v20
	s_nop 1
	v_addc_co_u32_e32 v93, vcc, 0, v21, vcc
	global_load_dword v150, v[92:93], off
	v_add_co_u32_e32 v92, vcc, 0x1b0000, v20
	s_nop 1
	v_addc_co_u32_e32 v93, vcc, 0, v21, vcc
	global_load_dword v151, v[92:93], off
	v_add_co_u32_e32 v92, vcc, 0x1bc000, v20
	s_nop 1
	v_addc_co_u32_e32 v93, vcc, 0, v21, vcc
	global_load_dword v152, v[92:93], off
	v_add_co_u32_e32 v92, vcc, 0x1c8000, v20
	s_nop 1
	v_addc_co_u32_e32 v93, vcc, 0, v21, vcc
	global_load_dword v153, v[92:93], off
	v_add_co_u32_e32 v92, vcc, 0x1d4000, v20
	s_nop 1
	v_addc_co_u32_e32 v93, vcc, 0, v21, vcc
	global_load_dword v154, v[92:93], off
	v_add_co_u32_e32 v92, vcc, 0x1e0000, v20
	s_nop 1
	v_addc_co_u32_e32 v93, vcc, 0, v21, vcc
	global_load_dword v155, v[92:93], off
	v_add_co_u32_e32 v92, vcc, 0x1ec000, v20
	s_nop 1
	v_addc_co_u32_e32 v93, vcc, 0, v21, vcc
	global_load_dword v156, v[92:93], off
	v_add_co_u32_e32 v92, vcc, 0x1f8000, v20
	s_nop 1
	v_addc_co_u32_e32 v93, vcc, 0, v21, vcc
	global_load_dword v157, v[92:93], off
	v_add_co_u32_e32 v92, vcc, 0x204000, v20
	s_nop 1
	v_addc_co_u32_e32 v93, vcc, 0, v21, vcc
	global_load_dword v158, v[92:93], off
	v_add_co_u32_e32 v92, vcc, 0x210000, v20
	s_nop 1
	v_addc_co_u32_e32 v93, vcc, 0, v21, vcc
	global_load_dword v159, v[92:93], off
	v_add_co_u32_e32 v92, vcc, 0x21c000, v20
	s_nop 1
	v_addc_co_u32_e32 v93, vcc, 0, v21, vcc
	global_load_dword v160, v[92:93], off
	v_add_co_u32_e32 v92, vcc, 0x228000, v20
	s_nop 1
	v_addc_co_u32_e32 v93, vcc, 0, v21, vcc
	global_load_dword v161, v[92:93], off
	v_add_co_u32_e32 v92, vcc, 0x234000, v20
	s_nop 1
	v_addc_co_u32_e32 v93, vcc, 0, v21, vcc
	global_load_dword v162, v[92:93], off
	v_add_co_u32_e32 v92, vcc, 0x240000, v20
	s_nop 1
	v_addc_co_u32_e32 v93, vcc, 0, v21, vcc
	global_load_dword v163, v[92:93], off
	ds_read_b128 v[212:215], v38 offset:16
	ds_read_b128 v[216:219], v38 offset:2064
	ds_read_b128 v[220:223], v38 offset:4112
	ds_read_b128 v[224:227], v38 offset:6160
	ds_read_b128 v[228:231], v38 offset:8208
	ds_read_b128 v[232:235], v38 offset:10256
	ds_read_b128 v[236:239], v38 offset:12304
	ds_read_b128 v[240:243], v38 offset:14352
	ds_read_b128 v[244:247], v38 offset:16400
	s_waitcnt lgkmcnt(9)
	v_mul_f32_e32 v90, v101, v55
	v_mul_f32_e32 v91, v103, v57
	v_fmac_f32_e32 v90, v100, v54
	v_fmac_f32_e32 v91, v102, v56
	v_add_f32_e32 v90, v90, v91
	v_add_f32_e32 v22, v22, v90
	v_mul_f32_e32 v90, v101, v59
	v_mul_f32_e32 v91, v103, v61
	v_fmac_f32_e32 v90, v100, v58
	v_fmac_f32_e32 v91, v102, v60
	v_add_f32_e32 v90, v90, v91
	v_add_f32_e32 v23, v23, v90
	v_mul_f32_e32 v90, v101, v63
	v_mul_f32_e32 v91, v103, v65
	v_fmac_f32_e32 v90, v100, v62
	v_fmac_f32_e32 v91, v102, v64
	v_add_f32_e32 v90, v90, v91
	v_add_f32_e32 v24, v24, v90
	v_mul_f32_e32 v90, v101, v67
	v_mul_f32_e32 v91, v103, v69
	v_fmac_f32_e32 v90, v100, v66
	v_fmac_f32_e32 v91, v102, v68
	v_add_f32_e32 v90, v90, v91
	v_add_f32_e32 v25, v25, v90
	v_mul_f32_e32 v90, v101, v71
	v_mul_f32_e32 v91, v103, v73
	v_fmac_f32_e32 v90, v100, v70
	v_fmac_f32_e32 v91, v102, v72
	v_add_f32_e32 v90, v90, v91
	v_add_f32_e32 v26, v26, v90
	v_mul_f32_e32 v90, v101, v75
	v_mul_f32_e32 v91, v103, v77
	v_fmac_f32_e32 v90, v100, v74
	v_fmac_f32_e32 v91, v102, v76
	v_add_f32_e32 v90, v90, v91
	v_add_f32_e32 v27, v27, v90
	v_mul_f32_e32 v90, v101, v79
	v_mul_f32_e32 v91, v103, v81
	v_fmac_f32_e32 v90, v100, v78
	v_fmac_f32_e32 v91, v102, v80
	v_add_f32_e32 v90, v90, v91
	v_add_f32_e32 v28, v28, v90
	v_mul_f32_e32 v90, v101, v83
	v_mul_f32_e32 v91, v103, v85
	v_fmac_f32_e32 v90, v100, v82
	v_fmac_f32_e32 v91, v102, v84
	v_add_f32_e32 v90, v90, v91
	v_add_f32_e32 v29, v29, v90
	v_mul_f32_e32 v90, v101, v87
	v_mul_f32_e32 v91, v103, v89
	v_fmac_f32_e32 v90, v100, v86
	v_fmac_f32_e32 v91, v102, v88
	v_add_f32_e32 v90, v90, v91
	v_add_f32_e32 v0, v0, v90
	ds_read_b128 v[54:57], v38 offset:32
	ds_read_b128 v[58:61], v38 offset:2080
	ds_read_b128 v[62:65], v38 offset:4128
	ds_read_b128 v[66:69], v38 offset:6176
	ds_read_b128 v[70:73], v38 offset:8224
	ds_read_b128 v[74:77], v38 offset:10272
	ds_read_b128 v[78:81], v38 offset:12320
	ds_read_b128 v[82:85], v38 offset:14368
	ds_read_b128 v[86:89], v38 offset:16416
	s_waitcnt lgkmcnt(9)
	v_mul_f32_e32 v90, v105, v213
	v_mul_f32_e32 v91, v107, v215
	v_fmac_f32_e32 v90, v104, v212
	v_fmac_f32_e32 v91, v106, v214
	v_add_f32_e32 v90, v90, v91
	v_add_f32_e32 v22, v22, v90
	v_mul_f32_e32 v90, v105, v217
	v_mul_f32_e32 v91, v107, v219
	v_fmac_f32_e32 v90, v104, v216
	v_fmac_f32_e32 v91, v106, v218
	v_add_f32_e32 v90, v90, v91
	v_add_f32_e32 v23, v23, v90
	v_mul_f32_e32 v90, v105, v221
	v_mul_f32_e32 v91, v107, v223
	v_fmac_f32_e32 v90, v104, v220
	v_fmac_f32_e32 v91, v106, v222
	v_add_f32_e32 v90, v90, v91
	v_add_f32_e32 v24, v24, v90
	v_mul_f32_e32 v90, v105, v225
	v_mul_f32_e32 v91, v107, v227
	v_fmac_f32_e32 v90, v104, v224
	v_fmac_f32_e32 v91, v106, v226
	v_add_f32_e32 v90, v90, v91
	v_add_f32_e32 v25, v25, v90
	v_mul_f32_e32 v90, v105, v229
	v_mul_f32_e32 v91, v107, v231
	v_fmac_f32_e32 v90, v104, v228
	v_fmac_f32_e32 v91, v106, v230
	v_add_f32_e32 v90, v90, v91
	v_add_f32_e32 v26, v26, v90
	v_mul_f32_e32 v90, v105, v233
	v_mul_f32_e32 v91, v107, v235
	v_fmac_f32_e32 v90, v104, v232
	v_fmac_f32_e32 v91, v106, v234
	v_add_f32_e32 v90, v90, v91
	v_add_f32_e32 v27, v27, v90
	v_mul_f32_e32 v90, v105, v237
	v_mul_f32_e32 v91, v107, v239
	v_fmac_f32_e32 v90, v104, v236
	v_fmac_f32_e32 v91, v106, v238
	v_add_f32_e32 v90, v90, v91
	v_add_f32_e32 v28, v28, v90
	v_mul_f32_e32 v90, v105, v241
	v_mul_f32_e32 v91, v107, v243
	v_fmac_f32_e32 v90, v104, v240
	v_fmac_f32_e32 v91, v106, v242
	v_add_f32_e32 v90, v90, v91
	v_add_f32_e32 v29, v29, v90
	v_mul_f32_e32 v90, v105, v245
	v_mul_f32_e32 v91, v107, v247
	v_fmac_f32_e32 v90, v104, v244
	v_fmac_f32_e32 v91, v106, v246
	v_add_f32_e32 v90, v90, v91
	v_add_f32_e32 v0, v0, v90
	ds_read_b128 v[212:215], v38 offset:48
	ds_read_b128 v[216:219], v38 offset:2096
	ds_read_b128 v[220:223], v38 offset:4144
	ds_read_b128 v[224:227], v38 offset:6192
	ds_read_b128 v[228:231], v38 offset:8240
	ds_read_b128 v[232:235], v38 offset:10288
	ds_read_b128 v[236:239], v38 offset:12336
	ds_read_b128 v[240:243], v38 offset:14384
	ds_read_b128 v[244:247], v38 offset:16432
	s_waitcnt lgkmcnt(9)
	v_mul_f32_e32 v90, v109, v55
	v_mul_f32_e32 v91, v111, v57
	v_fmac_f32_e32 v90, v108, v54
	v_fmac_f32_e32 v91, v110, v56
	v_add_f32_e32 v90, v90, v91
	v_add_f32_e32 v22, v22, v90
	v_mul_f32_e32 v90, v109, v59
	v_mul_f32_e32 v91, v111, v61
	v_fmac_f32_e32 v90, v108, v58
	v_fmac_f32_e32 v91, v110, v60
	v_add_f32_e32 v90, v90, v91
	v_add_f32_e32 v23, v23, v90
	v_mul_f32_e32 v90, v109, v63
	v_mul_f32_e32 v91, v111, v65
	v_fmac_f32_e32 v90, v108, v62
	v_fmac_f32_e32 v91, v110, v64
	v_add_f32_e32 v90, v90, v91
	v_add_f32_e32 v24, v24, v90
	v_mul_f32_e32 v90, v109, v67
	v_mul_f32_e32 v91, v111, v69
	v_fmac_f32_e32 v90, v108, v66
	v_fmac_f32_e32 v91, v110, v68
	v_add_f32_e32 v90, v90, v91
	v_add_f32_e32 v25, v25, v90
	v_mul_f32_e32 v90, v109, v71
	v_mul_f32_e32 v91, v111, v73
	v_fmac_f32_e32 v90, v108, v70
	v_fmac_f32_e32 v91, v110, v72
	v_add_f32_e32 v90, v90, v91
	v_add_f32_e32 v26, v26, v90
	v_mul_f32_e32 v90, v109, v75
	v_mul_f32_e32 v91, v111, v77
	v_fmac_f32_e32 v90, v108, v74
	v_fmac_f32_e32 v91, v110, v76
	v_add_f32_e32 v90, v90, v91
	v_add_f32_e32 v27, v27, v90
	v_mul_f32_e32 v90, v109, v79
	v_mul_f32_e32 v91, v111, v81
	v_fmac_f32_e32 v90, v108, v78
	v_fmac_f32_e32 v91, v110, v80
	v_add_f32_e32 v90, v90, v91
	v_add_f32_e32 v28, v28, v90
	v_mul_f32_e32 v90, v109, v83
	v_mul_f32_e32 v91, v111, v85
	v_fmac_f32_e32 v90, v108, v82
	v_fmac_f32_e32 v91, v110, v84
	v_add_f32_e32 v90, v90, v91
	v_add_f32_e32 v29, v29, v90
	v_mul_f32_e32 v90, v109, v87
	v_mul_f32_e32 v91, v111, v89
	v_fmac_f32_e32 v90, v108, v86
	v_fmac_f32_e32 v91, v110, v88
	v_add_f32_e32 v90, v90, v91
	v_add_f32_e32 v0, v0, v90
	ds_read_b128 v[54:57], v38 offset:64
	ds_read_b128 v[58:61], v38 offset:2112
	ds_read_b128 v[62:65], v38 offset:4160
	ds_read_b128 v[66:69], v38 offset:6208
	ds_read_b128 v[70:73], v38 offset:8256
	ds_read_b128 v[74:77], v38 offset:10304
	ds_read_b128 v[78:81], v38 offset:12352
	ds_read_b128 v[82:85], v38 offset:14400
	ds_read_b128 v[86:89], v38 offset:16448
	s_waitcnt lgkmcnt(9)
	v_mul_f32_e32 v90, v113, v213
	v_mul_f32_e32 v91, v115, v215
	v_fmac_f32_e32 v90, v112, v212
	v_fmac_f32_e32 v91, v114, v214
	v_add_f32_e32 v90, v90, v91
	v_add_f32_e32 v22, v22, v90
	v_mul_f32_e32 v90, v113, v217
	v_mul_f32_e32 v91, v115, v219
	v_fmac_f32_e32 v90, v112, v216
	v_fmac_f32_e32 v91, v114, v218
	v_add_f32_e32 v90, v90, v91
	v_add_f32_e32 v23, v23, v90
	v_mul_f32_e32 v90, v113, v221
	v_mul_f32_e32 v91, v115, v223
	v_fmac_f32_e32 v90, v112, v220
	v_fmac_f32_e32 v91, v114, v222
	v_add_f32_e32 v90, v90, v91
	v_add_f32_e32 v24, v24, v90
	v_mul_f32_e32 v90, v113, v225
	v_mul_f32_e32 v91, v115, v227
	v_fmac_f32_e32 v90, v112, v224
	v_fmac_f32_e32 v91, v114, v226
	v_add_f32_e32 v90, v90, v91
	v_add_f32_e32 v25, v25, v90
	v_mul_f32_e32 v90, v113, v229
	v_mul_f32_e32 v91, v115, v231
	v_fmac_f32_e32 v90, v112, v228
	v_fmac_f32_e32 v91, v114, v230
	v_add_f32_e32 v90, v90, v91
	v_add_f32_e32 v26, v26, v90
	v_mul_f32_e32 v90, v113, v233
	v_mul_f32_e32 v91, v115, v235
	v_fmac_f32_e32 v90, v112, v232
	v_fmac_f32_e32 v91, v114, v234
	v_add_f32_e32 v90, v90, v91
	v_add_f32_e32 v27, v27, v90
	v_mul_f32_e32 v90, v113, v237
	v_mul_f32_e32 v91, v115, v239
	v_fmac_f32_e32 v90, v112, v236
	v_fmac_f32_e32 v91, v114, v238
	v_add_f32_e32 v90, v90, v91
	v_add_f32_e32 v28, v28, v90
	v_mul_f32_e32 v90, v113, v241
	v_mul_f32_e32 v91, v115, v243
	v_fmac_f32_e32 v90, v112, v240
	v_fmac_f32_e32 v91, v114, v242
	v_add_f32_e32 v90, v90, v91
	v_add_f32_e32 v29, v29, v90
	v_mul_f32_e32 v90, v113, v245
	v_mul_f32_e32 v91, v115, v247
	v_fmac_f32_e32 v90, v112, v244
	v_fmac_f32_e32 v91, v114, v246
	v_add_f32_e32 v90, v90, v91
	v_add_f32_e32 v0, v0, v90
	s_waitcnt vmcnt(32)
	ds_read_b128 v[212:215], v38 offset:80
	ds_read_b128 v[216:219], v38 offset:2128
	ds_read_b128 v[220:223], v38 offset:4176
	ds_read_b128 v[224:227], v38 offset:6224
	ds_read_b128 v[228:231], v38 offset:8272
	ds_read_b128 v[232:235], v38 offset:10320
	ds_read_b128 v[236:239], v38 offset:12368
	ds_read_b128 v[240:243], v38 offset:14416
	ds_read_b128 v[244:247], v38 offset:16464
	s_waitcnt lgkmcnt(9)
	v_mul_f32_e32 v90, v117, v55
	v_mul_f32_e32 v91, v119, v57
	v_fmac_f32_e32 v90, v116, v54
	v_fmac_f32_e32 v91, v118, v56
	v_add_f32_e32 v90, v90, v91
	v_add_f32_e32 v22, v22, v90
	v_mul_f32_e32 v90, v117, v59
	v_mul_f32_e32 v91, v119, v61
	v_fmac_f32_e32 v90, v116, v58
	v_fmac_f32_e32 v91, v118, v60
	v_add_f32_e32 v90, v90, v91
	v_add_f32_e32 v23, v23, v90
	v_mul_f32_e32 v90, v117, v63
	v_mul_f32_e32 v91, v119, v65
	v_fmac_f32_e32 v90, v116, v62
	v_fmac_f32_e32 v91, v118, v64
	v_add_f32_e32 v90, v90, v91
	v_add_f32_e32 v24, v24, v90
	v_mul_f32_e32 v90, v117, v67
	v_mul_f32_e32 v91, v119, v69
	v_fmac_f32_e32 v90, v116, v66
	v_fmac_f32_e32 v91, v118, v68
	v_add_f32_e32 v90, v90, v91
	v_add_f32_e32 v25, v25, v90
	v_mul_f32_e32 v90, v117, v71
	v_mul_f32_e32 v91, v119, v73
	v_fmac_f32_e32 v90, v116, v70
	v_fmac_f32_e32 v91, v118, v72
	v_add_f32_e32 v90, v90, v91
	v_add_f32_e32 v26, v26, v90
	v_mul_f32_e32 v90, v117, v75
	v_mul_f32_e32 v91, v119, v77
	v_fmac_f32_e32 v90, v116, v74
	v_fmac_f32_e32 v91, v118, v76
	v_add_f32_e32 v90, v90, v91
	v_add_f32_e32 v27, v27, v90
	v_mul_f32_e32 v90, v117, v79
	v_mul_f32_e32 v91, v119, v81
	v_fmac_f32_e32 v90, v116, v78
	v_fmac_f32_e32 v91, v118, v80
	v_add_f32_e32 v90, v90, v91
	v_add_f32_e32 v28, v28, v90
	v_mul_f32_e32 v90, v117, v83
	v_mul_f32_e32 v91, v119, v85
	v_fmac_f32_e32 v90, v116, v82
	v_fmac_f32_e32 v91, v118, v84
	v_add_f32_e32 v90, v90, v91
	v_add_f32_e32 v29, v29, v90
	v_mul_f32_e32 v90, v117, v87
	v_mul_f32_e32 v91, v119, v89
	v_fmac_f32_e32 v90, v116, v86
	v_fmac_f32_e32 v91, v118, v88
	v_add_f32_e32 v90, v90, v91
	v_add_f32_e32 v0, v0, v90
	ds_read_b128 v[54:57], v38 offset:96
	ds_read_b128 v[58:61], v38 offset:2144
	ds_read_b128 v[62:65], v38 offset:4192
	ds_read_b128 v[66:69], v38 offset:6240
	ds_read_b128 v[70:73], v38 offset:8288
	ds_read_b128 v[74:77], v38 offset:10336
	ds_read_b128 v[78:81], v38 offset:12384
	ds_read_b128 v[82:85], v38 offset:14432
	ds_read_b128 v[86:89], v38 offset:16480
	s_waitcnt lgkmcnt(9)
	v_mul_f32_e32 v90, v121, v213
	v_mul_f32_e32 v91, v123, v215
	v_fmac_f32_e32 v90, v120, v212
	v_fmac_f32_e32 v91, v122, v214
	v_add_f32_e32 v90, v90, v91
	v_add_f32_e32 v22, v22, v90
	v_mul_f32_e32 v90, v121, v217
	v_mul_f32_e32 v91, v123, v219
	v_fmac_f32_e32 v90, v120, v216
	v_fmac_f32_e32 v91, v122, v218
	v_add_f32_e32 v90, v90, v91
	v_add_f32_e32 v23, v23, v90
	v_mul_f32_e32 v90, v121, v221
	v_mul_f32_e32 v91, v123, v223
	v_fmac_f32_e32 v90, v120, v220
	v_fmac_f32_e32 v91, v122, v222
	v_add_f32_e32 v90, v90, v91
	v_add_f32_e32 v24, v24, v90
	v_mul_f32_e32 v90, v121, v225
	v_mul_f32_e32 v91, v123, v227
	v_fmac_f32_e32 v90, v120, v224
	v_fmac_f32_e32 v91, v122, v226
	v_add_f32_e32 v90, v90, v91
	v_add_f32_e32 v25, v25, v90
	v_mul_f32_e32 v90, v121, v229
	v_mul_f32_e32 v91, v123, v231
	v_fmac_f32_e32 v90, v120, v228
	v_fmac_f32_e32 v91, v122, v230
	v_add_f32_e32 v90, v90, v91
	v_add_f32_e32 v26, v26, v90
	v_mul_f32_e32 v90, v121, v233
	v_mul_f32_e32 v91, v123, v235
	v_fmac_f32_e32 v90, v120, v232
	v_fmac_f32_e32 v91, v122, v234
	v_add_f32_e32 v90, v90, v91
	v_add_f32_e32 v27, v27, v90
	v_mul_f32_e32 v90, v121, v237
	v_mul_f32_e32 v91, v123, v239
	v_fmac_f32_e32 v90, v120, v236
	v_fmac_f32_e32 v91, v122, v238
	v_add_f32_e32 v90, v90, v91
	v_add_f32_e32 v28, v28, v90
	v_mul_f32_e32 v90, v121, v241
	v_mul_f32_e32 v91, v123, v243
	v_fmac_f32_e32 v90, v120, v240
	v_fmac_f32_e32 v91, v122, v242
	v_add_f32_e32 v90, v90, v91
	v_add_f32_e32 v29, v29, v90
	v_mul_f32_e32 v90, v121, v245
	v_mul_f32_e32 v91, v123, v247
	v_fmac_f32_e32 v90, v120, v244
	v_fmac_f32_e32 v91, v122, v246
	v_add_f32_e32 v90, v90, v91
	v_add_f32_e32 v0, v0, v90
	ds_read_b128 v[212:215], v38 offset:112
	ds_read_b128 v[216:219], v38 offset:2160
	ds_read_b128 v[220:223], v38 offset:4208
	ds_read_b128 v[224:227], v38 offset:6256
	ds_read_b128 v[228:231], v38 offset:8304
	ds_read_b128 v[232:235], v38 offset:10352
	ds_read_b128 v[236:239], v38 offset:12400
	ds_read_b128 v[240:243], v38 offset:14448
	ds_read_b128 v[244:247], v38 offset:16496
	s_waitcnt lgkmcnt(9)
	v_mul_f32_e32 v90, v125, v55
	v_mul_f32_e32 v91, v127, v57
	v_fmac_f32_e32 v90, v124, v54
	v_fmac_f32_e32 v91, v126, v56
	v_add_f32_e32 v90, v90, v91
	v_add_f32_e32 v22, v22, v90
	v_mul_f32_e32 v90, v125, v59
	v_mul_f32_e32 v91, v127, v61
	v_fmac_f32_e32 v90, v124, v58
	v_fmac_f32_e32 v91, v126, v60
	v_add_f32_e32 v90, v90, v91
	v_add_f32_e32 v23, v23, v90
	v_mul_f32_e32 v90, v125, v63
	v_mul_f32_e32 v91, v127, v65
	v_fmac_f32_e32 v90, v124, v62
	v_fmac_f32_e32 v91, v126, v64
	v_add_f32_e32 v90, v90, v91
	v_add_f32_e32 v24, v24, v90
	v_mul_f32_e32 v90, v125, v67
	v_mul_f32_e32 v91, v127, v69
	v_fmac_f32_e32 v90, v124, v66
	v_fmac_f32_e32 v91, v126, v68
	v_add_f32_e32 v90, v90, v91
	v_add_f32_e32 v25, v25, v90
	v_mul_f32_e32 v90, v125, v71
	v_mul_f32_e32 v91, v127, v73
	v_fmac_f32_e32 v90, v124, v70
	v_fmac_f32_e32 v91, v126, v72
	v_add_f32_e32 v90, v90, v91
	v_add_f32_e32 v26, v26, v90
	v_mul_f32_e32 v90, v125, v75
	v_mul_f32_e32 v91, v127, v77
	v_fmac_f32_e32 v90, v124, v74
	v_fmac_f32_e32 v91, v126, v76
	v_add_f32_e32 v90, v90, v91
	v_add_f32_e32 v27, v27, v90
	v_mul_f32_e32 v90, v125, v79
	v_mul_f32_e32 v91, v127, v81
	v_fmac_f32_e32 v90, v124, v78
	v_fmac_f32_e32 v91, v126, v80
	v_add_f32_e32 v90, v90, v91
	v_add_f32_e32 v28, v28, v90
	v_mul_f32_e32 v90, v125, v83
	v_mul_f32_e32 v91, v127, v85
	v_fmac_f32_e32 v90, v124, v82
	v_fmac_f32_e32 v91, v126, v84
	v_add_f32_e32 v90, v90, v91
	v_add_f32_e32 v29, v29, v90
	v_mul_f32_e32 v90, v125, v87
	v_mul_f32_e32 v91, v127, v89
	v_fmac_f32_e32 v90, v124, v86
	v_fmac_f32_e32 v91, v126, v88
	v_add_f32_e32 v90, v90, v91
	v_add_f32_e32 v0, v0, v90
	ds_read_b128 v[54:57], v38 offset:128
	ds_read_b128 v[58:61], v38 offset:2176
	ds_read_b128 v[62:65], v38 offset:4224
	ds_read_b128 v[66:69], v38 offset:6272
	ds_read_b128 v[70:73], v38 offset:8320
	ds_read_b128 v[74:77], v38 offset:10368
	ds_read_b128 v[78:81], v38 offset:12416
	ds_read_b128 v[82:85], v38 offset:14464
	ds_read_b128 v[86:89], v38 offset:16512
	s_waitcnt lgkmcnt(9)
	v_mul_f32_e32 v90, v129, v213
	v_mul_f32_e32 v91, v131, v215
	v_fmac_f32_e32 v90, v128, v212
	v_fmac_f32_e32 v91, v130, v214
	v_add_f32_e32 v90, v90, v91
	v_add_f32_e32 v22, v22, v90
	v_mul_f32_e32 v90, v129, v217
	v_mul_f32_e32 v91, v131, v219
	v_fmac_f32_e32 v90, v128, v216
	v_fmac_f32_e32 v91, v130, v218
	v_add_f32_e32 v90, v90, v91
	v_add_f32_e32 v23, v23, v90
	v_mul_f32_e32 v90, v129, v221
	v_mul_f32_e32 v91, v131, v223
	v_fmac_f32_e32 v90, v128, v220
	v_fmac_f32_e32 v91, v130, v222
	v_add_f32_e32 v90, v90, v91
	v_add_f32_e32 v24, v24, v90
	v_mul_f32_e32 v90, v129, v225
	v_mul_f32_e32 v91, v131, v227
	v_fmac_f32_e32 v90, v128, v224
	v_fmac_f32_e32 v91, v130, v226
	v_add_f32_e32 v90, v90, v91
	v_add_f32_e32 v25, v25, v90
	v_mul_f32_e32 v90, v129, v229
	v_mul_f32_e32 v91, v131, v231
	v_fmac_f32_e32 v90, v128, v228
	v_fmac_f32_e32 v91, v130, v230
	v_add_f32_e32 v90, v90, v91
	v_add_f32_e32 v26, v26, v90
	v_mul_f32_e32 v90, v129, v233
	v_mul_f32_e32 v91, v131, v235
	v_fmac_f32_e32 v90, v128, v232
	v_fmac_f32_e32 v91, v130, v234
	v_add_f32_e32 v90, v90, v91
	v_add_f32_e32 v27, v27, v90
	v_mul_f32_e32 v90, v129, v237
	v_mul_f32_e32 v91, v131, v239
	v_fmac_f32_e32 v90, v128, v236
	v_fmac_f32_e32 v91, v130, v238
	v_add_f32_e32 v90, v90, v91
	v_add_f32_e32 v28, v28, v90
	v_mul_f32_e32 v90, v129, v241
	v_mul_f32_e32 v91, v131, v243
	v_fmac_f32_e32 v90, v128, v240
	v_fmac_f32_e32 v91, v130, v242
	v_add_f32_e32 v90, v90, v91
	v_add_f32_e32 v29, v29, v90
	v_mul_f32_e32 v90, v129, v245
	v_mul_f32_e32 v91, v131, v247
	v_fmac_f32_e32 v90, v128, v244
	v_fmac_f32_e32 v91, v130, v246
	v_add_f32_e32 v90, v90, v91
	v_add_f32_e32 v0, v0, v90
	s_waitcnt vmcnt(16)
	ds_read_b128 v[212:215], v38 offset:144
	ds_read_b128 v[216:219], v38 offset:2192
	ds_read_b128 v[220:223], v38 offset:4240
	ds_read_b128 v[224:227], v38 offset:6288
	ds_read_b128 v[228:231], v38 offset:8336
	ds_read_b128 v[232:235], v38 offset:10384
	ds_read_b128 v[236:239], v38 offset:12432
	ds_read_b128 v[240:243], v38 offset:14480
	ds_read_b128 v[244:247], v38 offset:16528
	s_waitcnt lgkmcnt(9)
	v_mul_f32_e32 v90, v133, v55
	v_mul_f32_e32 v91, v135, v57
	v_fmac_f32_e32 v90, v132, v54
	v_fmac_f32_e32 v91, v134, v56
	v_add_f32_e32 v90, v90, v91
	v_add_f32_e32 v22, v22, v90
	v_mul_f32_e32 v90, v133, v59
	v_mul_f32_e32 v91, v135, v61
	v_fmac_f32_e32 v90, v132, v58
	v_fmac_f32_e32 v91, v134, v60
	v_add_f32_e32 v90, v90, v91
	v_add_f32_e32 v23, v23, v90
	v_mul_f32_e32 v90, v133, v63
	v_mul_f32_e32 v91, v135, v65
	v_fmac_f32_e32 v90, v132, v62
	v_fmac_f32_e32 v91, v134, v64
	v_add_f32_e32 v90, v90, v91
	v_add_f32_e32 v24, v24, v90
	v_mul_f32_e32 v90, v133, v67
	v_mul_f32_e32 v91, v135, v69
	v_fmac_f32_e32 v90, v132, v66
	v_fmac_f32_e32 v91, v134, v68
	v_add_f32_e32 v90, v90, v91
	v_add_f32_e32 v25, v25, v90
	v_mul_f32_e32 v90, v133, v71
	v_mul_f32_e32 v91, v135, v73
	v_fmac_f32_e32 v90, v132, v70
	v_fmac_f32_e32 v91, v134, v72
	v_add_f32_e32 v90, v90, v91
	v_add_f32_e32 v26, v26, v90
	v_mul_f32_e32 v90, v133, v75
	v_mul_f32_e32 v91, v135, v77
	v_fmac_f32_e32 v90, v132, v74
	v_fmac_f32_e32 v91, v134, v76
	v_add_f32_e32 v90, v90, v91
	v_add_f32_e32 v27, v27, v90
	v_mul_f32_e32 v90, v133, v79
	v_mul_f32_e32 v91, v135, v81
	v_fmac_f32_e32 v90, v132, v78
	v_fmac_f32_e32 v91, v134, v80
	v_add_f32_e32 v90, v90, v91
	v_add_f32_e32 v28, v28, v90
	v_mul_f32_e32 v90, v133, v83
	v_mul_f32_e32 v91, v135, v85
	v_fmac_f32_e32 v90, v132, v82
	v_fmac_f32_e32 v91, v134, v84
	v_add_f32_e32 v90, v90, v91
	v_add_f32_e32 v29, v29, v90
	v_mul_f32_e32 v90, v133, v87
	v_mul_f32_e32 v91, v135, v89
	v_fmac_f32_e32 v90, v132, v86
	v_fmac_f32_e32 v91, v134, v88
	v_add_f32_e32 v90, v90, v91
	v_add_f32_e32 v0, v0, v90
	ds_read_b128 v[54:57], v38 offset:160
	ds_read_b128 v[58:61], v38 offset:2208
	ds_read_b128 v[62:65], v38 offset:4256
	ds_read_b128 v[66:69], v38 offset:6304
	ds_read_b128 v[70:73], v38 offset:8352
	ds_read_b128 v[74:77], v38 offset:10400
	ds_read_b128 v[78:81], v38 offset:12448
	ds_read_b128 v[82:85], v38 offset:14496
	ds_read_b128 v[86:89], v38 offset:16544
	s_waitcnt lgkmcnt(9)
	v_mul_f32_e32 v90, v137, v213
	v_mul_f32_e32 v91, v139, v215
	v_fmac_f32_e32 v90, v136, v212
	v_fmac_f32_e32 v91, v138, v214
	v_add_f32_e32 v90, v90, v91
	v_add_f32_e32 v22, v22, v90
	v_mul_f32_e32 v90, v137, v217
	v_mul_f32_e32 v91, v139, v219
	v_fmac_f32_e32 v90, v136, v216
	v_fmac_f32_e32 v91, v138, v218
	v_add_f32_e32 v90, v90, v91
	v_add_f32_e32 v23, v23, v90
	v_mul_f32_e32 v90, v137, v221
	v_mul_f32_e32 v91, v139, v223
	v_fmac_f32_e32 v90, v136, v220
	v_fmac_f32_e32 v91, v138, v222
	v_add_f32_e32 v90, v90, v91
	v_add_f32_e32 v24, v24, v90
	v_mul_f32_e32 v90, v137, v225
	v_mul_f32_e32 v91, v139, v227
	v_fmac_f32_e32 v90, v136, v224
	v_fmac_f32_e32 v91, v138, v226
	v_add_f32_e32 v90, v90, v91
	v_add_f32_e32 v25, v25, v90
	v_mul_f32_e32 v90, v137, v229
	v_mul_f32_e32 v91, v139, v231
	v_fmac_f32_e32 v90, v136, v228
	v_fmac_f32_e32 v91, v138, v230
	v_add_f32_e32 v90, v90, v91
	v_add_f32_e32 v26, v26, v90
	v_mul_f32_e32 v90, v137, v233
	v_mul_f32_e32 v91, v139, v235
	v_fmac_f32_e32 v90, v136, v232
	v_fmac_f32_e32 v91, v138, v234
	v_add_f32_e32 v90, v90, v91
	v_add_f32_e32 v27, v27, v90
	v_mul_f32_e32 v90, v137, v237
	v_mul_f32_e32 v91, v139, v239
	v_fmac_f32_e32 v90, v136, v236
	v_fmac_f32_e32 v91, v138, v238
	v_add_f32_e32 v90, v90, v91
	v_add_f32_e32 v28, v28, v90
	v_mul_f32_e32 v90, v137, v241
	v_mul_f32_e32 v91, v139, v243
	v_fmac_f32_e32 v90, v136, v240
	v_fmac_f32_e32 v91, v138, v242
	v_add_f32_e32 v90, v90, v91
	v_add_f32_e32 v29, v29, v90
	v_mul_f32_e32 v90, v137, v245
	v_mul_f32_e32 v91, v139, v247
	v_fmac_f32_e32 v90, v136, v244
	v_fmac_f32_e32 v91, v138, v246
	v_add_f32_e32 v90, v90, v91
	v_add_f32_e32 v0, v0, v90
	ds_read_b128 v[212:215], v38 offset:176
	ds_read_b128 v[216:219], v38 offset:2224
	ds_read_b128 v[220:223], v38 offset:4272
	ds_read_b128 v[224:227], v38 offset:6320
	ds_read_b128 v[228:231], v38 offset:8368
	ds_read_b128 v[232:235], v38 offset:10416
	ds_read_b128 v[236:239], v38 offset:12464
	ds_read_b128 v[240:243], v38 offset:14512
	ds_read_b128 v[244:247], v38 offset:16560
	s_waitcnt lgkmcnt(9)
	v_mul_f32_e32 v90, v141, v55
	v_mul_f32_e32 v91, v143, v57
	v_fmac_f32_e32 v90, v140, v54
	v_fmac_f32_e32 v91, v142, v56
	v_add_f32_e32 v90, v90, v91
	v_add_f32_e32 v22, v22, v90
	v_mul_f32_e32 v90, v141, v59
	v_mul_f32_e32 v91, v143, v61
	v_fmac_f32_e32 v90, v140, v58
	v_fmac_f32_e32 v91, v142, v60
	v_add_f32_e32 v90, v90, v91
	v_add_f32_e32 v23, v23, v90
	v_mul_f32_e32 v90, v141, v63
	v_mul_f32_e32 v91, v143, v65
	v_fmac_f32_e32 v90, v140, v62
	v_fmac_f32_e32 v91, v142, v64
	v_add_f32_e32 v90, v90, v91
	v_add_f32_e32 v24, v24, v90
	v_mul_f32_e32 v90, v141, v67
	v_mul_f32_e32 v91, v143, v69
	v_fmac_f32_e32 v90, v140, v66
	v_fmac_f32_e32 v91, v142, v68
	v_add_f32_e32 v90, v90, v91
	v_add_f32_e32 v25, v25, v90
	v_mul_f32_e32 v90, v141, v71
	v_mul_f32_e32 v91, v143, v73
	v_fmac_f32_e32 v90, v140, v70
	v_fmac_f32_e32 v91, v142, v72
	v_add_f32_e32 v90, v90, v91
	v_add_f32_e32 v26, v26, v90
	v_mul_f32_e32 v90, v141, v75
	v_mul_f32_e32 v91, v143, v77
	v_fmac_f32_e32 v90, v140, v74
	v_fmac_f32_e32 v91, v142, v76
	v_add_f32_e32 v90, v90, v91
	v_add_f32_e32 v27, v27, v90
	v_mul_f32_e32 v90, v141, v79
	v_mul_f32_e32 v91, v143, v81
	v_fmac_f32_e32 v90, v140, v78
	v_fmac_f32_e32 v91, v142, v80
	v_add_f32_e32 v90, v90, v91
	v_add_f32_e32 v28, v28, v90
	v_mul_f32_e32 v90, v141, v83
	v_mul_f32_e32 v91, v143, v85
	v_fmac_f32_e32 v90, v140, v82
	v_fmac_f32_e32 v91, v142, v84
	v_add_f32_e32 v90, v90, v91
	v_add_f32_e32 v29, v29, v90
	v_mul_f32_e32 v90, v141, v87
	v_mul_f32_e32 v91, v143, v89
	v_fmac_f32_e32 v90, v140, v86
	v_fmac_f32_e32 v91, v142, v88
	v_add_f32_e32 v90, v90, v91
	v_add_f32_e32 v0, v0, v90
	ds_read_b128 v[54:57], v38 offset:192
	ds_read_b128 v[58:61], v38 offset:2240
	ds_read_b128 v[62:65], v38 offset:4288
	ds_read_b128 v[66:69], v38 offset:6336
	ds_read_b128 v[70:73], v38 offset:8384
	ds_read_b128 v[74:77], v38 offset:10432
	ds_read_b128 v[78:81], v38 offset:12480
	ds_read_b128 v[82:85], v38 offset:14528
	ds_read_b128 v[86:89], v38 offset:16576
	s_waitcnt lgkmcnt(9)
	v_mul_f32_e32 v90, v145, v213
	v_mul_f32_e32 v91, v147, v215
	v_fmac_f32_e32 v90, v144, v212
	v_fmac_f32_e32 v91, v146, v214
	v_add_f32_e32 v90, v90, v91
	v_add_f32_e32 v22, v22, v90
	v_mul_f32_e32 v90, v145, v217
	v_mul_f32_e32 v91, v147, v219
	v_fmac_f32_e32 v90, v144, v216
	v_fmac_f32_e32 v91, v146, v218
	v_add_f32_e32 v90, v90, v91
	v_add_f32_e32 v23, v23, v90
	v_mul_f32_e32 v90, v145, v221
	v_mul_f32_e32 v91, v147, v223
	v_fmac_f32_e32 v90, v144, v220
	v_fmac_f32_e32 v91, v146, v222
	v_add_f32_e32 v90, v90, v91
	v_add_f32_e32 v24, v24, v90
	v_mul_f32_e32 v90, v145, v225
	v_mul_f32_e32 v91, v147, v227
	v_fmac_f32_e32 v90, v144, v224
	v_fmac_f32_e32 v91, v146, v226
	v_add_f32_e32 v90, v90, v91
	v_add_f32_e32 v25, v25, v90
	v_mul_f32_e32 v90, v145, v229
	v_mul_f32_e32 v91, v147, v231
	v_fmac_f32_e32 v90, v144, v228
	v_fmac_f32_e32 v91, v146, v230
	v_add_f32_e32 v90, v90, v91
	v_add_f32_e32 v26, v26, v90
	v_mul_f32_e32 v90, v145, v233
	v_mul_f32_e32 v91, v147, v235
	v_fmac_f32_e32 v90, v144, v232
	v_fmac_f32_e32 v91, v146, v234
	v_add_f32_e32 v90, v90, v91
	v_add_f32_e32 v27, v27, v90
	v_mul_f32_e32 v90, v145, v237
	v_mul_f32_e32 v91, v147, v239
	v_fmac_f32_e32 v90, v144, v236
	v_fmac_f32_e32 v91, v146, v238
	v_add_f32_e32 v90, v90, v91
	v_add_f32_e32 v28, v28, v90
	v_mul_f32_e32 v90, v145, v241
	v_mul_f32_e32 v91, v147, v243
	v_fmac_f32_e32 v90, v144, v240
	v_fmac_f32_e32 v91, v146, v242
	v_add_f32_e32 v90, v90, v91
	v_add_f32_e32 v29, v29, v90
	v_mul_f32_e32 v90, v145, v245
	v_mul_f32_e32 v91, v147, v247
	v_fmac_f32_e32 v90, v144, v244
	v_fmac_f32_e32 v91, v146, v246
	v_add_f32_e32 v90, v90, v91
	v_add_f32_e32 v0, v0, v90
	s_waitcnt vmcnt(0)
	ds_read_b128 v[212:215], v38 offset:208
	ds_read_b128 v[216:219], v38 offset:2256
	ds_read_b128 v[220:223], v38 offset:4304
	ds_read_b128 v[224:227], v38 offset:6352
	ds_read_b128 v[228:231], v38 offset:8400
	ds_read_b128 v[232:235], v38 offset:10448
	ds_read_b128 v[236:239], v38 offset:12496
	ds_read_b128 v[240:243], v38 offset:14544
	ds_read_b128 v[244:247], v38 offset:16592
	s_waitcnt lgkmcnt(9)
	v_mul_f32_e32 v90, v149, v55
	v_mul_f32_e32 v91, v151, v57
	v_fmac_f32_e32 v90, v148, v54
	v_fmac_f32_e32 v91, v150, v56
	v_add_f32_e32 v90, v90, v91
	v_add_f32_e32 v22, v22, v90
	v_mul_f32_e32 v90, v149, v59
	v_mul_f32_e32 v91, v151, v61
	v_fmac_f32_e32 v90, v148, v58
	v_fmac_f32_e32 v91, v150, v60
	v_add_f32_e32 v90, v90, v91
	v_add_f32_e32 v23, v23, v90
	v_mul_f32_e32 v90, v149, v63
	v_mul_f32_e32 v91, v151, v65
	v_fmac_f32_e32 v90, v148, v62
	v_fmac_f32_e32 v91, v150, v64
	v_add_f32_e32 v90, v90, v91
	v_add_f32_e32 v24, v24, v90
	v_mul_f32_e32 v90, v149, v67
	v_mul_f32_e32 v91, v151, v69
	v_fmac_f32_e32 v90, v148, v66
	v_fmac_f32_e32 v91, v150, v68
	v_add_f32_e32 v90, v90, v91
	v_add_f32_e32 v25, v25, v90
	v_mul_f32_e32 v90, v149, v71
	v_mul_f32_e32 v91, v151, v73
	v_fmac_f32_e32 v90, v148, v70
	v_fmac_f32_e32 v91, v150, v72
	v_add_f32_e32 v90, v90, v91
	v_add_f32_e32 v26, v26, v90
	v_mul_f32_e32 v90, v149, v75
	v_mul_f32_e32 v91, v151, v77
	v_fmac_f32_e32 v90, v148, v74
	v_fmac_f32_e32 v91, v150, v76
	v_add_f32_e32 v90, v90, v91
	v_add_f32_e32 v27, v27, v90
	v_mul_f32_e32 v90, v149, v79
	v_mul_f32_e32 v91, v151, v81
	v_fmac_f32_e32 v90, v148, v78
	v_fmac_f32_e32 v91, v150, v80
	v_add_f32_e32 v90, v90, v91
	v_add_f32_e32 v28, v28, v90
	v_mul_f32_e32 v90, v149, v83
	v_mul_f32_e32 v91, v151, v85
	v_fmac_f32_e32 v90, v148, v82
	v_fmac_f32_e32 v91, v150, v84
	v_add_f32_e32 v90, v90, v91
	v_add_f32_e32 v29, v29, v90
	v_mul_f32_e32 v90, v149, v87
	v_mul_f32_e32 v91, v151, v89
	v_fmac_f32_e32 v90, v148, v86
	v_fmac_f32_e32 v91, v150, v88
	v_add_f32_e32 v90, v90, v91
	v_add_f32_e32 v0, v0, v90
	ds_read_b128 v[54:57], v38 offset:224
	ds_read_b128 v[58:61], v38 offset:2272
	ds_read_b128 v[62:65], v38 offset:4320
	ds_read_b128 v[66:69], v38 offset:6368
	ds_read_b128 v[70:73], v38 offset:8416
	ds_read_b128 v[74:77], v38 offset:10464
	ds_read_b128 v[78:81], v38 offset:12512
	ds_read_b128 v[82:85], v38 offset:14560
	ds_read_b128 v[86:89], v38 offset:16608
	s_waitcnt lgkmcnt(9)
	v_mul_f32_e32 v90, v153, v213
	v_mul_f32_e32 v91, v155, v215
	v_fmac_f32_e32 v90, v152, v212
	v_fmac_f32_e32 v91, v154, v214
	v_add_f32_e32 v90, v90, v91
	v_add_f32_e32 v22, v22, v90
	v_mul_f32_e32 v90, v153, v217
	v_mul_f32_e32 v91, v155, v219
	v_fmac_f32_e32 v90, v152, v216
	v_fmac_f32_e32 v91, v154, v218
	v_add_f32_e32 v90, v90, v91
	v_add_f32_e32 v23, v23, v90
	v_mul_f32_e32 v90, v153, v221
	v_mul_f32_e32 v91, v155, v223
	v_fmac_f32_e32 v90, v152, v220
	v_fmac_f32_e32 v91, v154, v222
	v_add_f32_e32 v90, v90, v91
	v_add_f32_e32 v24, v24, v90
	v_mul_f32_e32 v90, v153, v225
	v_mul_f32_e32 v91, v155, v227
	v_fmac_f32_e32 v90, v152, v224
	v_fmac_f32_e32 v91, v154, v226
	v_add_f32_e32 v90, v90, v91
	v_add_f32_e32 v25, v25, v90
	v_mul_f32_e32 v90, v153, v229
	v_mul_f32_e32 v91, v155, v231
	v_fmac_f32_e32 v90, v152, v228
	v_fmac_f32_e32 v91, v154, v230
	v_add_f32_e32 v90, v90, v91
	v_add_f32_e32 v26, v26, v90
	v_mul_f32_e32 v90, v153, v233
	v_mul_f32_e32 v91, v155, v235
	v_fmac_f32_e32 v90, v152, v232
	v_fmac_f32_e32 v91, v154, v234
	v_add_f32_e32 v90, v90, v91
	v_add_f32_e32 v27, v27, v90
	v_mul_f32_e32 v90, v153, v237
	v_mul_f32_e32 v91, v155, v239
	v_fmac_f32_e32 v90, v152, v236
	v_fmac_f32_e32 v91, v154, v238
	v_add_f32_e32 v90, v90, v91
	v_add_f32_e32 v28, v28, v90
	v_mul_f32_e32 v90, v153, v241
	v_mul_f32_e32 v91, v155, v243
	v_fmac_f32_e32 v90, v152, v240
	v_fmac_f32_e32 v91, v154, v242
	v_add_f32_e32 v90, v90, v91
	v_add_f32_e32 v29, v29, v90
	v_mul_f32_e32 v90, v153, v245
	v_mul_f32_e32 v91, v155, v247
	v_fmac_f32_e32 v90, v152, v244
	v_fmac_f32_e32 v91, v154, v246
	v_add_f32_e32 v90, v90, v91
	v_add_f32_e32 v0, v0, v90
	ds_read_b128 v[212:215], v38 offset:240
	ds_read_b128 v[216:219], v38 offset:2288
	ds_read_b128 v[220:223], v38 offset:4336
	ds_read_b128 v[224:227], v38 offset:6384
	ds_read_b128 v[228:231], v38 offset:8432
	ds_read_b128 v[232:235], v38 offset:10480
	ds_read_b128 v[236:239], v38 offset:12528
	ds_read_b128 v[240:243], v38 offset:14576
	ds_read_b128 v[244:247], v38 offset:16624
	s_waitcnt lgkmcnt(9)
	v_mul_f32_e32 v90, v157, v55
	v_mul_f32_e32 v91, v159, v57
	v_fmac_f32_e32 v90, v156, v54
	v_fmac_f32_e32 v91, v158, v56
	v_add_f32_e32 v90, v90, v91
	v_add_f32_e32 v22, v22, v90
	v_mul_f32_e32 v90, v157, v59
	v_mul_f32_e32 v91, v159, v61
	v_fmac_f32_e32 v90, v156, v58
	v_fmac_f32_e32 v91, v158, v60
	v_add_f32_e32 v90, v90, v91
	v_add_f32_e32 v23, v23, v90
	v_mul_f32_e32 v90, v157, v63
	v_mul_f32_e32 v91, v159, v65
	v_fmac_f32_e32 v90, v156, v62
	v_fmac_f32_e32 v91, v158, v64
	v_add_f32_e32 v90, v90, v91
	v_add_f32_e32 v24, v24, v90
	v_mul_f32_e32 v90, v157, v67
	v_mul_f32_e32 v91, v159, v69
	v_fmac_f32_e32 v90, v156, v66
	v_fmac_f32_e32 v91, v158, v68
	v_add_f32_e32 v90, v90, v91
	v_add_f32_e32 v25, v25, v90
	v_mul_f32_e32 v90, v157, v71
	v_mul_f32_e32 v91, v159, v73
	v_fmac_f32_e32 v90, v156, v70
	v_fmac_f32_e32 v91, v158, v72
	v_add_f32_e32 v90, v90, v91
	v_add_f32_e32 v26, v26, v90
	v_mul_f32_e32 v90, v157, v75
	v_mul_f32_e32 v91, v159, v77
	v_fmac_f32_e32 v90, v156, v74
	v_fmac_f32_e32 v91, v158, v76
	v_add_f32_e32 v90, v90, v91
	v_add_f32_e32 v27, v27, v90
	v_mul_f32_e32 v90, v157, v79
	v_mul_f32_e32 v91, v159, v81
	v_fmac_f32_e32 v90, v156, v78
	v_fmac_f32_e32 v91, v158, v80
	v_add_f32_e32 v90, v90, v91
	v_add_f32_e32 v28, v28, v90
	v_mul_f32_e32 v90, v157, v83
	v_mul_f32_e32 v91, v159, v85
	v_fmac_f32_e32 v90, v156, v82
	v_fmac_f32_e32 v91, v158, v84
	v_add_f32_e32 v90, v90, v91
	v_add_f32_e32 v29, v29, v90
	v_mul_f32_e32 v90, v157, v87
	v_mul_f32_e32 v91, v159, v89
	v_fmac_f32_e32 v90, v156, v86
	v_fmac_f32_e32 v91, v158, v88
	v_add_f32_e32 v90, v90, v91
	v_add_f32_e32 v0, v0, v90
	s_waitcnt lgkmcnt(0)
	v_mul_f32_e32 v90, v161, v213
	v_mul_f32_e32 v91, v163, v215
	v_fmac_f32_e32 v90, v160, v212
	v_fmac_f32_e32 v91, v162, v214
	v_add_f32_e32 v90, v90, v91
	v_add_f32_e32 v22, v22, v90
	v_mul_f32_e32 v90, v161, v217
	v_mul_f32_e32 v91, v163, v219
	v_fmac_f32_e32 v90, v160, v216
	v_fmac_f32_e32 v91, v162, v218
	v_add_f32_e32 v90, v90, v91
	v_add_f32_e32 v23, v23, v90
	v_mul_f32_e32 v90, v161, v221
	v_mul_f32_e32 v91, v163, v223
	v_fmac_f32_e32 v90, v160, v220
	v_fmac_f32_e32 v91, v162, v222
	v_add_f32_e32 v90, v90, v91
	v_add_f32_e32 v24, v24, v90
	v_mul_f32_e32 v90, v161, v225
	v_mul_f32_e32 v91, v163, v227
	v_fmac_f32_e32 v90, v160, v224
	v_fmac_f32_e32 v91, v162, v226
	v_add_f32_e32 v90, v90, v91
	v_add_f32_e32 v25, v25, v90
	v_mul_f32_e32 v90, v161, v229
	v_mul_f32_e32 v91, v163, v231
	v_fmac_f32_e32 v90, v160, v228
	v_fmac_f32_e32 v91, v162, v230
	v_add_f32_e32 v90, v90, v91
	v_add_f32_e32 v26, v26, v90
	v_mul_f32_e32 v90, v161, v233
	v_mul_f32_e32 v91, v163, v235
	v_fmac_f32_e32 v90, v160, v232
	v_fmac_f32_e32 v91, v162, v234
	v_add_f32_e32 v90, v90, v91
	v_add_f32_e32 v27, v27, v90
	v_mul_f32_e32 v90, v161, v237
	v_mul_f32_e32 v91, v163, v239
	v_fmac_f32_e32 v90, v160, v236
	v_fmac_f32_e32 v91, v162, v238
	v_add_f32_e32 v90, v90, v91
	v_add_f32_e32 v28, v28, v90
	v_mul_f32_e32 v90, v161, v241
	v_mul_f32_e32 v91, v163, v243
	v_fmac_f32_e32 v90, v160, v240
	v_fmac_f32_e32 v91, v162, v242
	v_add_f32_e32 v90, v90, v91
	v_add_f32_e32 v29, v29, v90
	v_mul_f32_e32 v90, v161, v245
	v_mul_f32_e32 v91, v163, v247
	v_fmac_f32_e32 v90, v160, v244
	v_fmac_f32_e32 v91, v162, v246
	v_add_f32_e32 v90, v90, v91
	v_add_f32_e32 v0, v0, v90
	v_add_u32_e32 v2, 0xa000, v37
	ds_write2_b32 v2, v22, v23 offset1:32
	ds_write2_b32 v2, v24, v25 offset0:64 offset1:96
	ds_write2_b32 v2, v26, v27 offset0:128 offset1:160
	ds_write2_b32 v2, v28, v29 offset0:192 offset1:224
	ds_write_b32 v37, v0 offset:41984
	s_waitcnt lgkmcnt(0)
	s_barrier
	s_and_saveexec_b64 s[22:23], s[38:39]
	s_cbranch_execz .LBB0_1020
	s_mul_i32 s25, s24, 0x1800
	s_add_i32 s26, s25, s0
	v_or_b32_e32 v2, s26, v14
	v_readlane_b32 s56, v253, 6
	v_ashrrev_i32_e32 v3, 31, v2
	v_readlane_b32 s58, v253, 8
	v_readlane_b32 s59, v253, 9
	v_readlane_b32 s64, v253, 14
	v_readlane_b32 s65, v253, 15
	s_mul_hi_i32 s25, s24, 9
	s_mul_i32 s24, s24, 9
	v_readlane_b32 s64, v253, 49
	v_lshl_add_u64 v[2:3], v[2:3], 2, s[58:59]
	v_lshl_add_u64 v[4:5], s[0:1], 2, v[16:17]
	s_mov_b64 s[0:1], 0
	v_mov_b32_e32 v0, v184
	v_readlane_b32 s57, v253, 7
	v_readlane_b32 s60, v253, 10
	v_readlane_b32 s61, v253, 11
	v_readlane_b32 s62, v253, 12
	v_readlane_b32 s63, v253, 13
	v_readlane_b32 s66, v253, 16
	v_readlane_b32 s67, v253, 17
	v_readlane_b32 s68, v253, 18
	v_readlane_b32 s69, v253, 19
	v_readlane_b32 s70, v253, 20
	v_readlane_b32 s71, v253, 21
	v_readlane_b32 s65, v253, 50
